# GEMM unit transitions: accumulators zeroed with 64 v_mov_b64 instead of 127 v_mov_b32
# speedup vs baseline: 1.0065x; 1.0057x over previous
;     __device__ __forceinline__ bool next(int i, Unit& u) const { if (i != 0 || c >= n) return false; u.pm = pm; u.pn = c & 3; return true; }
; template <class Epi, class Sched, bool ALIGN_EPI = false, bool SP2 = false>
; __device__ __forceinline__ void gemm_phase(PG8_LAS unsigned char* lds, const Gemm g, const Sched& S, const Epi& E) {
;     ...
;         const bool has_next = S.next(ui + 1, nxt);
;         const char* nA = has_next ? (const char*)g.A + (size_t)nxt.pm * tstepA : cA; const char* nB = has_next ? (const char*)g.Bt + (size_t)nxt.pn * tstepB : cB;
;     ...
; #pragma unroll
;         for (int a = 0; a < 2; ++a)
; #pragma unroll
;             for (int b = 0; b < 2; ++b)
; #pragma unroll
;                 for (int m = 0; m < 4; ++m)
; #pragma unroll
;                     for (int n = 0; n < 2; ++n) acc[a][b][m][n] = (f32x4){0.f, 0.f, 0.f, 0.f};
;         cur = nxt; cA = nA; cB = nB; ++ui;
.LBB0_182:
	s_ashr_i32 s15, s14, 31
	s_lshl_b64 s[16:17], s[14:15], 19
	v_readlane_b32 s18, v254, 18
	v_readlane_b32 s19, v254, 19
	s_add_u32 s16, s18, s16
	s_addc_u32 s17, s19, s17
	s_and_b64 s[18:19], s[2:3], exec
	s_cselect_b32 s1, s17, s21
	s_cselect_b32 s5, s16, s20
	s_ashr_i32 s13, s12, 31
	v_readlane_b32 s48, v253, 2
	s_lshl_b64 s[18:19], s[12:13], 19
	v_readlane_b32 s50, v253, 4
	v_readlane_b32 s51, v253, 5
	s_add_u32 s18, s50, s18
	s_addc_u32 s19, s51, s19
	s_and_b64 s[24:25], s[2:3], exec
	s_cselect_b32 s13, s19, s23
	s_cselect_b32 s15, s18, s22
	s_add_u32 s20, s20, 0x40080
	s_addc_u32 s21, s21, 0
	s_add_u32 s62, s22, 0x100
	v_mov_b32_e32 v0, 0
	s_addc_u32 s63, s23, 0
	s_mov_b32 s64, -2
	v_mov_b64_e32 v[0:1], 0
	v_mov_b64_e32 v[2:3], 0
	v_mov_b64_e32 v[4:5], 0
	v_mov_b64_e32 v[6:7], 0
	v_mov_b64_e32 v[8:9], 0
	v_mov_b64_e32 v[10:11], 0
	v_mov_b64_e32 v[12:13], 0
	v_mov_b64_e32 v[14:15], 0
	v_mov_b64_e32 v[16:17], 0
	v_mov_b64_e32 v[18:19], 0
	v_mov_b64_e32 v[20:21], 0
	v_mov_b64_e32 v[22:23], 0
	v_mov_b64_e32 v[24:25], 0
	v_mov_b64_e32 v[26:27], 0
	v_mov_b64_e32 v[28:29], 0
	v_mov_b64_e32 v[30:31], 0
	v_mov_b64_e32 v[32:33], 0
	v_mov_b64_e32 v[34:35], 0
	v_mov_b64_e32 v[36:37], 0
	v_mov_b64_e32 v[38:39], 0
	v_mov_b64_e32 v[40:41], 0
	v_mov_b64_e32 v[42:43], 0
	v_mov_b64_e32 v[44:45], 0
	v_mov_b64_e32 v[46:47], 0
	v_mov_b64_e32 v[48:49], 0
	v_mov_b64_e32 v[50:51], 0
	v_mov_b64_e32 v[52:53], 0
	v_mov_b64_e32 v[54:55], 0
	v_mov_b64_e32 v[56:57], 0
	v_mov_b64_e32 v[58:59], 0
	v_mov_b64_e32 v[60:61], 0
	v_mov_b64_e32 v[62:63], 0
	v_mov_b64_e32 v[64:65], 0
	v_mov_b64_e32 v[66:67], 0
	v_mov_b64_e32 v[68:69], 0
	v_mov_b64_e32 v[70:71], 0
	v_mov_b64_e32 v[72:73], 0
	v_mov_b64_e32 v[74:75], 0
	v_mov_b64_e32 v[76:77], 0
	v_mov_b64_e32 v[78:79], 0
	v_mov_b64_e32 v[80:81], 0
	v_mov_b64_e32 v[82:83], 0
	v_mov_b64_e32 v[84:85], 0
	v_mov_b64_e32 v[86:87], 0
	v_mov_b64_e32 v[88:89], 0
	v_mov_b64_e32 v[90:91], 0
	v_mov_b64_e32 v[92:93], 0
	v_mov_b64_e32 v[94:95], 0
	v_mov_b64_e32 v[96:97], 0
	v_mov_b64_e32 v[98:99], 0
	v_mov_b64_e32 v[100:101], 0
	v_mov_b64_e32 v[102:103], 0
	v_mov_b64_e32 v[104:105], 0
	v_mov_b64_e32 v[106:107], 0
	v_mov_b64_e32 v[108:109], 0
	v_mov_b64_e32 v[110:111], 0
	v_mov_b64_e32 v[112:113], 0
	v_mov_b64_e32 v[114:115], 0
	v_mov_b64_e32 v[116:117], 0
	v_mov_b64_e32 v[118:119], 0
	v_mov_b64_e32 v[120:121], 0
	v_mov_b64_e32 v[122:123], 0
	v_mov_b64_e32 v[124:125], 0
	v_mov_b64_e32 v[126:127], 0
	v_readlane_b32 s49, v253, 3

;     __device__ __forceinline__ bool next(int i, Unit& u) const { if (i != 0 || c >= n) return false; u.pm = pm; u.pn = c & 3; return true; }
; template <class Epi, class Sched, bool ALIGN_EPI = false, bool SP2 = false>
; __device__ __forceinline__ void gemm_phase(PG8_LAS unsigned char* lds, const Gemm g, const Sched& S, const Epi& E) {
;     ...
;         const bool has_next = S.next(ui + 1, nxt);
;         const char* nA = has_next ? (const char*)g.A + (size_t)nxt.pm * tstepA : cA; const char* nB = has_next ? (const char*)g.Bt + (size_t)nxt.pn * tstepB : cB;
;     ...
; #pragma unroll
;         for (int a = 0; a < 2; ++a)
; #pragma unroll
;             for (int b = 0; b < 2; ++b)
; #pragma unroll
;                 for (int m = 0; m < 4; ++m)
; #pragma unroll
;                     for (int n = 0; n < 2; ++n) acc[a][b][m][n] = (f32x4){0.f, 0.f, 0.f, 0.f};
;         cur = nxt; cA = nA; cB = nB; ++ui;
.LBB0_863:
	s_ashr_i32 s13, s12, 31
	s_lshl_b64 s[16:17], s[12:13], 20
	v_readlane_b32 s13, v253, 24
	s_add_u32 s16, s13, s16
	v_readlane_b32 s13, v253, 26
	s_addc_u32 s17, s13, s17
	s_and_b64 s[0:1], s[0:1], exec
	s_cselect_b32 s13, s17, s23
	s_cselect_b32 s19, s16, s22
	s_add_u32 s65, s22, 0x100
	v_mov_b32_e32 v0, 0
	s_addc_u32 s72, s23, 0
	s_mov_b32 s73, -2
	v_mov_b64_e32 v[0:1], 0
	v_mov_b64_e32 v[2:3], 0
	v_mov_b64_e32 v[4:5], 0
	v_mov_b64_e32 v[6:7], 0
	v_mov_b64_e32 v[8:9], 0
	v_mov_b64_e32 v[10:11], 0
	v_mov_b64_e32 v[12:13], 0
	v_mov_b64_e32 v[14:15], 0
	v_mov_b64_e32 v[16:17], 0
	v_mov_b64_e32 v[18:19], 0
	v_mov_b64_e32 v[20:21], 0
	v_mov_b64_e32 v[22:23], 0
	v_mov_b64_e32 v[24:25], 0
	v_mov_b64_e32 v[26:27], 0
	v_mov_b64_e32 v[28:29], 0
	v_mov_b64_e32 v[30:31], 0
	v_mov_b64_e32 v[32:33], 0
	v_mov_b64_e32 v[34:35], 0
	v_mov_b64_e32 v[36:37], 0
	v_mov_b64_e32 v[38:39], 0
	v_mov_b64_e32 v[40:41], 0
	v_mov_b64_e32 v[42:43], 0
	v_mov_b64_e32 v[44:45], 0
	v_mov_b64_e32 v[46:47], 0
	v_mov_b64_e32 v[48:49], 0
	v_mov_b64_e32 v[50:51], 0
	v_mov_b64_e32 v[52:53], 0
	v_mov_b64_e32 v[54:55], 0
	v_mov_b64_e32 v[56:57], 0
	v_mov_b64_e32 v[58:59], 0
	v_mov_b64_e32 v[60:61], 0
	v_mov_b64_e32 v[62:63], 0
	v_mov_b64_e32 v[64:65], 0
	v_mov_b64_e32 v[66:67], 0
	v_mov_b64_e32 v[68:69], 0
	v_mov_b64_e32 v[70:71], 0
	v_mov_b64_e32 v[72:73], 0
	v_mov_b64_e32 v[74:75], 0
	v_mov_b64_e32 v[76:77], 0
	v_mov_b64_e32 v[78:79], 0
	v_mov_b64_e32 v[80:81], 0
	v_mov_b64_e32 v[82:83], 0
	v_mov_b64_e32 v[84:85], 0
	v_mov_b64_e32 v[86:87], 0
	v_mov_b64_e32 v[88:89], 0
	v_mov_b64_e32 v[90:91], 0
	v_mov_b64_e32 v[92:93], 0
	v_mov_b64_e32 v[94:95], 0
	v_mov_b64_e32 v[96:97], 0
	v_mov_b64_e32 v[98:99], 0
	v_mov_b64_e32 v[100:101], 0
	v_mov_b64_e32 v[102:103], 0
	v_mov_b64_e32 v[104:105], 0
	v_mov_b64_e32 v[106:107], 0
	v_mov_b64_e32 v[108:109], 0
	v_mov_b64_e32 v[110:111], 0
	v_mov_b64_e32 v[112:113], 0
	v_mov_b64_e32 v[114:115], 0
	v_mov_b64_e32 v[116:117], 0
	v_mov_b64_e32 v[118:119], 0
	v_mov_b64_e32 v[120:121], 0
	v_mov_b64_e32 v[122:123], 0
	v_mov_b64_e32 v[124:125], 0
	v_mov_b64_e32 v[126:127], 0

;     __device__ __forceinline__ bool next(int i, Unit& u) const { if (i != 0 || c >= n) return false; u.pm = pm; u.pn = c & 3; return true; }
; template <class Epi, class Sched, bool ALIGN_EPI = false, bool SP2 = false>
; __device__ __forceinline__ void gemm_phase(PG8_LAS unsigned char* lds, const Gemm g, const Sched& S, const Epi& E) {
;     ...
;         const bool has_next = S.next(ui + 1, nxt);
;         const char* nA = has_next ? (const char*)g.A + (size_t)nxt.pm * tstepA : cA; const char* nB = has_next ? (const char*)g.Bt + (size_t)nxt.pn * tstepB : cB;
;     ...
; #pragma unroll
;         for (int a = 0; a < 2; ++a)
; #pragma unroll
;             for (int b = 0; b < 2; ++b)
; #pragma unroll
;                 for (int m = 0; m < 4; ++m)
; #pragma unroll
;                     for (int n = 0; n < 2; ++n) acc[a][b][m][n] = (f32x4){0.f, 0.f, 0.f, 0.f};
;         cur = nxt; cA = nA; cB = nB; ++ui;
.LBB0_1104:
	s_ashr_i32 s17, s16, 31
	s_lshl_b64 s[20:21], s[16:17], 19
	v_readlane_b32 s48, v254, 18
	v_readlane_b32 s49, v254, 19
	s_add_u32 s92, s48, s20
	s_addc_u32 s93, s49, s21
	s_and_b64 s[20:21], s[2:3], exec
	s_cselect_b32 s1, s93, s19
	s_cselect_b32 s5, s92, s18
	s_ashr_i32 s11, s10, 31
	s_lshl_b64 s[20:21], s[10:11], 19
	v_readlane_b32 s11, v254, 2
	s_add_u32 s94, s11, s20
	v_readlane_b32 s11, v254, 3
	s_addc_u32 s95, s11, s21
	s_and_b64 s[20:21], s[2:3], exec
	s_cselect_b32 s11, s95, s43
	s_cselect_b32 s17, s94, s42
	s_add_u32 s96, s18, 0x40080
	s_addc_u32 s97, s19, 0
	s_add_u32 s25, s42, 0x100
	v_mov_b32_e32 v0, 0
	s_addc_u32 s27, s43, 0
	s_mov_b32 s42, -2
	v_mov_b64_e32 v[0:1], 0
	v_mov_b64_e32 v[2:3], 0
	v_mov_b64_e32 v[4:5], 0
	v_mov_b64_e32 v[6:7], 0
	v_mov_b64_e32 v[8:9], 0
	v_mov_b64_e32 v[10:11], 0
	v_mov_b64_e32 v[12:13], 0
	v_mov_b64_e32 v[14:15], 0
	v_mov_b64_e32 v[16:17], 0
	v_mov_b64_e32 v[18:19], 0
	v_mov_b64_e32 v[20:21], 0
	v_mov_b64_e32 v[22:23], 0
	v_mov_b64_e32 v[24:25], 0
	v_mov_b64_e32 v[26:27], 0
	v_mov_b64_e32 v[28:29], 0
	v_mov_b64_e32 v[30:31], 0
	v_mov_b64_e32 v[32:33], 0
	v_mov_b64_e32 v[34:35], 0
	v_mov_b64_e32 v[36:37], 0
	v_mov_b64_e32 v[38:39], 0
	v_mov_b64_e32 v[40:41], 0
	v_mov_b64_e32 v[42:43], 0
	v_mov_b64_e32 v[44:45], 0
	v_mov_b64_e32 v[46:47], 0
	v_mov_b64_e32 v[48:49], 0
	v_mov_b64_e32 v[50:51], 0
	v_mov_b64_e32 v[52:53], 0
	v_mov_b64_e32 v[54:55], 0
	v_mov_b64_e32 v[56:57], 0
	v_mov_b64_e32 v[58:59], 0
	v_mov_b64_e32 v[60:61], 0
	v_mov_b64_e32 v[62:63], 0
	v_mov_b64_e32 v[64:65], 0
	v_mov_b64_e32 v[66:67], 0
	v_mov_b64_e32 v[68:69], 0
	v_mov_b64_e32 v[70:71], 0
	v_mov_b64_e32 v[72:73], 0
	v_mov_b64_e32 v[74:75], 0
	v_mov_b64_e32 v[76:77], 0
	v_mov_b64_e32 v[78:79], 0
	v_mov_b64_e32 v[80:81], 0
	v_mov_b64_e32 v[82:83], 0
	v_mov_b64_e32 v[84:85], 0
	v_mov_b64_e32 v[86:87], 0
	v_mov_b64_e32 v[88:89], 0
	v_mov_b64_e32 v[90:91], 0
	v_mov_b64_e32 v[92:93], 0
	v_mov_b64_e32 v[94:95], 0
	v_mov_b64_e32 v[96:97], 0
	v_mov_b64_e32 v[98:99], 0
	v_mov_b64_e32 v[100:101], 0
	v_mov_b64_e32 v[102:103], 0
	v_mov_b64_e32 v[104:105], 0
	v_mov_b64_e32 v[106:107], 0
	v_mov_b64_e32 v[108:109], 0
	v_mov_b64_e32 v[110:111], 0
	v_mov_b64_e32 v[112:113], 0
	v_mov_b64_e32 v[114:115], 0
	v_mov_b64_e32 v[116:117], 0
	v_mov_b64_e32 v[118:119], 0
	v_mov_b64_e32 v[120:121], 0
	v_mov_b64_e32 v[122:123], 0
	v_mov_b64_e32 v[124:125], 0
	v_mov_b64_e32 v[126:127], 0

; template <class Epi, class Sched, bool ALIGN_EPI = false, bool SP2 = false>
; __device__ __forceinline__ void gemm_phase(PG8_LAS unsigned char* lds, const Gemm g, const Sched& S, const Epi& E) {
;     ...
; #pragma unroll
;         for (int a = 0; a < 2; ++a)
; #pragma unroll
;             for (int b = 0; b < 2; ++b)
; #pragma unroll
;                 for (int m = 0; m < 4; ++m)
; #pragma unroll
;                     for (int n = 0; n < 2; ++n) acc[a][b][m][n] = (f32x4){0.f, 0.f, 0.f, 0.f};
;         cur = nxt; cA = nA; cB = nB; ++ui;
.LBB0_1349:
	s_add_u32 s42, s42, 0x100
	v_mov_b32_e32 v0, 0
	s_addc_u32 s43, s43, 0
	s_mov_b32 s74, -2
	v_mov_b64_e32 v[0:1], 0
	v_mov_b64_e32 v[2:3], 0
	v_mov_b64_e32 v[4:5], 0
	v_mov_b64_e32 v[6:7], 0
	v_mov_b64_e32 v[8:9], 0
	v_mov_b64_e32 v[10:11], 0
	v_mov_b64_e32 v[12:13], 0
	v_mov_b64_e32 v[14:15], 0
	v_mov_b64_e32 v[16:17], 0
	v_mov_b64_e32 v[18:19], 0
	v_mov_b64_e32 v[20:21], 0
	v_mov_b64_e32 v[22:23], 0
	v_mov_b64_e32 v[24:25], 0
	v_mov_b64_e32 v[26:27], 0
	v_mov_b64_e32 v[28:29], 0
	v_mov_b64_e32 v[30:31], 0
	v_mov_b64_e32 v[32:33], 0
	v_mov_b64_e32 v[34:35], 0
	v_mov_b64_e32 v[36:37], 0
	v_mov_b64_e32 v[38:39], 0
	v_mov_b64_e32 v[40:41], 0
	v_mov_b64_e32 v[42:43], 0
	v_mov_b64_e32 v[44:45], 0
	v_mov_b64_e32 v[46:47], 0
	v_mov_b64_e32 v[48:49], 0
	v_mov_b64_e32 v[50:51], 0
	v_mov_b64_e32 v[52:53], 0
	v_mov_b64_e32 v[54:55], 0
	v_mov_b64_e32 v[56:57], 0
	v_mov_b64_e32 v[58:59], 0
	v_mov_b64_e32 v[60:61], 0
	v_mov_b64_e32 v[62:63], 0
	v_mov_b64_e32 v[64:65], 0
	v_mov_b64_e32 v[66:67], 0
	v_mov_b64_e32 v[68:69], 0
	v_mov_b64_e32 v[70:71], 0
	v_mov_b64_e32 v[72:73], 0
	v_mov_b64_e32 v[74:75], 0
	v_mov_b64_e32 v[76:77], 0
	v_mov_b64_e32 v[78:79], 0
	v_mov_b64_e32 v[80:81], 0
	v_mov_b64_e32 v[82:83], 0
	v_mov_b64_e32 v[84:85], 0
	v_mov_b64_e32 v[86:87], 0
	v_mov_b64_e32 v[88:89], 0
	v_mov_b64_e32 v[90:91], 0
	v_mov_b64_e32 v[92:93], 0
	v_mov_b64_e32 v[94:95], 0
	v_mov_b64_e32 v[96:97], 0
	v_mov_b64_e32 v[98:99], 0
	v_mov_b64_e32 v[100:101], 0
	v_mov_b64_e32 v[102:103], 0
	v_mov_b64_e32 v[104:105], 0
	v_mov_b64_e32 v[106:107], 0
	v_mov_b64_e32 v[108:109], 0
	v_mov_b64_e32 v[110:111], 0
	v_mov_b64_e32 v[112:113], 0
	v_mov_b64_e32 v[114:115], 0
	v_mov_b64_e32 v[116:117], 0
	v_mov_b64_e32 v[118:119], 0
	v_mov_b64_e32 v[120:121], 0
	v_mov_b64_e32 v[122:123], 0
	v_mov_b64_e32 v[124:125], 0
	v_mov_b64_e32 v[126:127], 0

;     __device__ __forceinline__ bool next(int i, Unit& u) const { if (i != 0 || c >= n) return false; u.pm = pm; u.pn = c & 3; return true; }
; template <class Epi, class Sched, bool ALIGN_EPI = false, bool SP2 = false>
; __device__ __forceinline__ void gemm_phase(PG8_LAS unsigned char* lds, const Gemm g, const Sched& S, const Epi& E) {
;     ...
;         const bool has_next = S.next(ui + 1, nxt);
;         const char* nA = has_next ? (const char*)g.A + (size_t)nxt.pm * tstepA : cA; const char* nB = has_next ? (const char*)g.Bt + (size_t)nxt.pn * tstepB : cB;
;     ...
; #pragma unroll
;         for (int a = 0; a < 2; ++a)
; #pragma unroll
;             for (int b = 0; b < 2; ++b)
; #pragma unroll
;                 for (int m = 0; m < 4; ++m)
; #pragma unroll
;                     for (int n = 0; n < 2; ++n) acc[a][b][m][n] = (f32x4){0.f, 0.f, 0.f, 0.f};
;         cur = nxt; cA = nA; cB = nB; ++ui;
.LBB0_1473:
	s_ashr_i32 s11, s10, 31
	s_lshl_b64 s[18:19], s[10:11], 17
	v_readlane_b32 s5, v254, 6
	s_add_u32 s92, s5, s18
	v_readlane_b32 s5, v254, 7
	s_addc_u32 s93, s5, s19
	s_and_b64 s[0:1], s[0:1], exec
	v_mov_b32_e32 v0, 0
	s_cselect_b32 s5, s93, s95
	s_cselect_b32 s11, s92, s94
	s_mov_b32 s18, 0
	s_mov_b64 s[0:1], -1
	s_mov_b64 s[42:43], 0
	v_mov_b64_e32 v[0:1], 0
	v_mov_b64_e32 v[2:3], 0
	v_mov_b64_e32 v[4:5], 0
	v_mov_b64_e32 v[6:7], 0
	v_mov_b64_e32 v[8:9], 0
	v_mov_b64_e32 v[10:11], 0
	v_mov_b64_e32 v[12:13], 0
	v_mov_b64_e32 v[14:15], 0
	v_mov_b64_e32 v[16:17], 0
	v_mov_b64_e32 v[18:19], 0
	v_mov_b64_e32 v[20:21], 0
	v_mov_b64_e32 v[22:23], 0
	v_mov_b64_e32 v[24:25], 0
	v_mov_b64_e32 v[26:27], 0
	v_mov_b64_e32 v[28:29], 0
	v_mov_b64_e32 v[30:31], 0
	v_mov_b64_e32 v[32:33], 0
	v_mov_b64_e32 v[34:35], 0
	v_mov_b64_e32 v[36:37], 0
	v_mov_b64_e32 v[38:39], 0
	v_mov_b64_e32 v[40:41], 0
	v_mov_b64_e32 v[42:43], 0
	v_mov_b64_e32 v[44:45], 0
	v_mov_b64_e32 v[46:47], 0
	v_mov_b64_e32 v[48:49], 0
	v_mov_b64_e32 v[50:51], 0
	v_mov_b64_e32 v[52:53], 0
	v_mov_b64_e32 v[54:55], 0
	v_mov_b64_e32 v[56:57], 0
	v_mov_b64_e32 v[58:59], 0
	v_mov_b64_e32 v[60:61], 0
	v_mov_b64_e32 v[62:63], 0
	v_mov_b64_e32 v[64:65], 0
	v_mov_b64_e32 v[66:67], 0
	v_mov_b64_e32 v[68:69], 0
	v_mov_b64_e32 v[70:71], 0
	v_mov_b64_e32 v[72:73], 0
	v_mov_b64_e32 v[74:75], 0
	v_mov_b64_e32 v[76:77], 0
	v_mov_b64_e32 v[78:79], 0
	v_mov_b64_e32 v[80:81], 0
	v_mov_b64_e32 v[82:83], 0
	v_mov_b64_e32 v[84:85], 0
	v_mov_b64_e32 v[86:87], 0
	v_mov_b64_e32 v[88:89], 0
	v_mov_b64_e32 v[90:91], 0
	v_mov_b64_e32 v[92:93], 0
	v_mov_b64_e32 v[94:95], 0
	v_mov_b64_e32 v[96:97], 0
	v_mov_b64_e32 v[98:99], 0
	v_mov_b64_e32 v[100:101], 0
	v_mov_b64_e32 v[102:103], 0
	v_mov_b64_e32 v[104:105], 0
	v_mov_b64_e32 v[106:107], 0
	v_mov_b64_e32 v[108:109], 0
	v_mov_b64_e32 v[110:111], 0
	v_mov_b64_e32 v[112:113], 0
	v_mov_b64_e32 v[114:115], 0
	v_mov_b64_e32 v[116:117], 0
	v_mov_b64_e32 v[118:119], 0
	v_mov_b64_e32 v[120:121], 0
	v_mov_b64_e32 v[122:123], 0
	v_mov_b64_e32 v[124:125], 0
	v_mov_b64_e32 v[126:127], 0

;     __device__ __forceinline__ bool next(int i, Unit& u) const { if (i != 0 || c >= n) return false; u.pm = pm; u.pn = c & 3; return true; }
; template <class Epi, class Sched, bool ALIGN_EPI = false, bool SP2 = false>
; __device__ __forceinline__ void gemm_phase(PG8_LAS unsigned char* lds, const Gemm g, const Sched& S, const Epi& E) {
;     ...
;         const bool has_next = S.next(ui + 1, nxt);
;         const char* nA = has_next ? (const char*)g.A + (size_t)nxt.pm * tstepA : cA; const char* nB = has_next ? (const char*)g.Bt + (size_t)nxt.pn * tstepB : cB;
;     ...
; #pragma unroll
;         for (int a = 0; a < 2; ++a)
; #pragma unroll
;             for (int b = 0; b < 2; ++b)
; #pragma unroll
;                 for (int m = 0; m < 4; ++m)
; #pragma unroll
;                     for (int n = 0; n < 2; ++n) acc[a][b][m][n] = (f32x4){0.f, 0.f, 0.f, 0.f};
;         cur = nxt; cA = nA; cB = nB; ++ui;
.LBB0_1966:
	s_ashr_i32 s9, s8, 31
	s_lshl_b64 s[10:11], s[8:9], 19
	v_readlane_b32 s18, v254, 18
	v_readlane_b32 s19, v254, 19
	s_add_u32 s10, s18, s10
	s_addc_u32 s11, s19, s11
	s_and_b64 s[18:19], s[2:3], exec
	s_cselect_b32 s9, s11, s97
	s_cselect_b32 s17, s10, s96
	s_ashr_i32 s7, s6, 31
	s_lshl_b64 s[18:19], s[6:7], 19
	v_readlane_b32 s7, v254, 8
	s_add_u32 s92, s7, s18
	v_readlane_b32 s7, v254, 9
	s_addc_u32 s93, s7, s19
	s_and_b64 s[18:19], s[2:3], exec
	s_cselect_b32 s7, s93, s43
	s_cselect_b32 s25, s92, s42
	s_add_u32 s96, s96, 0x40080
	s_addc_u32 s97, s97, 0
	s_add_u32 s27, s42, 0x100
	v_mov_b32_e32 v0, 0
	s_addc_u32 s42, s43, 0
	s_mov_b32 s43, -2
	v_mov_b64_e32 v[0:1], 0
	v_mov_b64_e32 v[2:3], 0
	v_mov_b64_e32 v[4:5], 0
	v_mov_b64_e32 v[6:7], 0
	v_mov_b64_e32 v[8:9], 0
	v_mov_b64_e32 v[10:11], 0
	v_mov_b64_e32 v[12:13], 0
	v_mov_b64_e32 v[14:15], 0
	v_mov_b64_e32 v[16:17], 0
	v_mov_b64_e32 v[18:19], 0
	v_mov_b64_e32 v[20:21], 0
	v_mov_b64_e32 v[22:23], 0
	v_mov_b64_e32 v[24:25], 0
	v_mov_b64_e32 v[26:27], 0
	v_mov_b64_e32 v[28:29], 0
	v_mov_b64_e32 v[30:31], 0
	v_mov_b64_e32 v[32:33], 0
	v_mov_b64_e32 v[34:35], 0
	v_mov_b64_e32 v[36:37], 0
	v_mov_b64_e32 v[38:39], 0
	v_mov_b64_e32 v[40:41], 0
	v_mov_b64_e32 v[42:43], 0
	v_mov_b64_e32 v[44:45], 0
	v_mov_b64_e32 v[46:47], 0
	v_mov_b64_e32 v[48:49], 0
	v_mov_b64_e32 v[50:51], 0
	v_mov_b64_e32 v[52:53], 0
	v_mov_b64_e32 v[54:55], 0
	v_mov_b64_e32 v[56:57], 0
	v_mov_b64_e32 v[58:59], 0
	v_mov_b64_e32 v[60:61], 0
	v_mov_b64_e32 v[62:63], 0
	v_mov_b64_e32 v[64:65], 0
	v_mov_b64_e32 v[66:67], 0
	v_mov_b64_e32 v[68:69], 0
	v_mov_b64_e32 v[70:71], 0
	v_mov_b64_e32 v[72:73], 0
	v_mov_b64_e32 v[74:75], 0
	v_mov_b64_e32 v[76:77], 0
	v_mov_b64_e32 v[78:79], 0
	v_mov_b64_e32 v[80:81], 0
	v_mov_b64_e32 v[82:83], 0
	v_mov_b64_e32 v[84:85], 0
	v_mov_b64_e32 v[86:87], 0
	v_mov_b64_e32 v[88:89], 0
	v_mov_b64_e32 v[90:91], 0
	v_mov_b64_e32 v[92:93], 0
	v_mov_b64_e32 v[94:95], 0
	v_mov_b64_e32 v[96:97], 0
	v_mov_b64_e32 v[98:99], 0
	v_mov_b64_e32 v[100:101], 0
	v_mov_b64_e32 v[102:103], 0
	v_mov_b64_e32 v[104:105], 0
	v_mov_b64_e32 v[106:107], 0
	v_mov_b64_e32 v[108:109], 0
	v_mov_b64_e32 v[110:111], 0
	v_mov_b64_e32 v[112:113], 0
	v_mov_b64_e32 v[114:115], 0
	v_mov_b64_e32 v[116:117], 0
	v_mov_b64_e32 v[118:119], 0
	v_mov_b64_e32 v[120:121], 0
	v_mov_b64_e32 v[122:123], 0
	v_mov_b64_e32 v[124:125], 0
	v_mov_b64_e32 v[126:127], 0

;     __device__ __forceinline__ bool next(int i, Unit& u) const { if (i != 0 || c >= n) return false; u.pm = pm; u.pn = c & 3; return true; }
; template <class Epi, class Sched, bool ALIGN_EPI = false, bool SP2 = false>
; __device__ __forceinline__ void gemm_phase(PG8_LAS unsigned char* lds, const Gemm g, const Sched& S, const Epi& E) {
;     ...
;         const bool has_next = S.next(ui + 1, nxt);
;         const char* nA = has_next ? (const char*)g.A + (size_t)nxt.pm * tstepA : cA; const char* nB = has_next ? (const char*)g.Bt + (size_t)nxt.pn * tstepB : cB;
;     ...
; #pragma unroll
;         for (int a = 0; a < 2; ++a)
; #pragma unroll
;             for (int b = 0; b < 2; ++b)
; #pragma unroll
;                 for (int m = 0; m < 4; ++m)
; #pragma unroll
;                     for (int n = 0; n < 2; ++n) acc[a][b][m][n] = (f32x4){0.f, 0.f, 0.f, 0.f};
;         cur = nxt; cA = nA; cB = nB; ++ui;
.LBB0_2176:
	s_ashr_i32 s97, s96, 31
	s_lshl_b64 s[16:17], s[96:97], 19
	v_readlane_b32 s20, v254, 18
	v_readlane_b32 s21, v254, 19
	s_add_u32 s16, s20, s16
	s_addc_u32 s17, s21, s17
	s_and_b64 s[20:21], s[2:3], exec
	s_cselect_b32 s1, s17, s43
	s_cselect_b32 s5, s16, s42
	s_ashr_i32 s93, s92, 31
	s_lshl_b64 s[20:21], s[92:93], 19
	s_add_u32 s94, s36, s20
	s_addc_u32 s95, s37, s21
	s_and_b64 s[20:21], s[2:3], exec
	s_cselect_b32 s25, s95, s19
	s_cselect_b32 s27, s94, s18
	s_add_u32 vcc_lo, s42, 0x40080
	s_addc_u32 vcc_hi, s43, 0
	s_add_u32 s42, s18, 0x100
	v_mov_b32_e32 v4, 0
	s_addc_u32 s43, s19, 0
	s_mov_b32 s75, -2
	v_mov_b64_e32 v[0:1], 0
	v_mov_b64_e32 v[2:3], 0
	v_mov_b64_e32 v[4:5], 0
	v_mov_b64_e32 v[6:7], 0
	v_mov_b64_e32 v[8:9], 0
	v_mov_b64_e32 v[10:11], 0
	v_mov_b64_e32 v[12:13], 0
	v_mov_b64_e32 v[14:15], 0
	v_mov_b64_e32 v[16:17], 0
	v_mov_b64_e32 v[18:19], 0
	v_mov_b64_e32 v[20:21], 0
	v_mov_b64_e32 v[22:23], 0
	v_mov_b64_e32 v[24:25], 0
	v_mov_b64_e32 v[26:27], 0
	v_mov_b64_e32 v[28:29], 0
	v_mov_b64_e32 v[30:31], 0
	v_mov_b64_e32 v[32:33], 0
	v_mov_b64_e32 v[34:35], 0
	v_mov_b64_e32 v[36:37], 0
	v_mov_b64_e32 v[38:39], 0
	v_mov_b64_e32 v[40:41], 0
	v_mov_b64_e32 v[42:43], 0
	v_mov_b64_e32 v[44:45], 0
	v_mov_b64_e32 v[46:47], 0
	v_mov_b64_e32 v[48:49], 0
	v_mov_b64_e32 v[50:51], 0
	v_mov_b64_e32 v[52:53], 0
	v_mov_b64_e32 v[54:55], 0
	v_mov_b64_e32 v[56:57], 0
	v_mov_b64_e32 v[58:59], 0
	v_mov_b64_e32 v[60:61], 0
	v_mov_b64_e32 v[62:63], 0
	v_mov_b64_e32 v[64:65], 0
	v_mov_b64_e32 v[66:67], 0
	v_mov_b64_e32 v[68:69], 0
	v_mov_b64_e32 v[70:71], 0
	v_mov_b64_e32 v[72:73], 0
	v_mov_b64_e32 v[74:75], 0
	v_mov_b64_e32 v[76:77], 0
	v_mov_b64_e32 v[78:79], 0
	v_mov_b64_e32 v[80:81], 0
	v_mov_b64_e32 v[82:83], 0
	v_mov_b64_e32 v[84:85], 0
	v_mov_b64_e32 v[86:87], 0
	v_mov_b64_e32 v[88:89], 0
	v_mov_b64_e32 v[90:91], 0
	v_mov_b64_e32 v[92:93], 0
	v_mov_b64_e32 v[94:95], 0
	v_mov_b64_e32 v[96:97], 0
	v_mov_b64_e32 v[98:99], 0
	v_mov_b64_e32 v[100:101], 0
	v_mov_b64_e32 v[102:103], 0
	v_mov_b64_e32 v[104:105], 0
	v_mov_b64_e32 v[106:107], 0
	v_mov_b64_e32 v[108:109], 0
	v_mov_b64_e32 v[110:111], 0
	v_mov_b64_e32 v[112:113], 0
	v_mov_b64_e32 v[114:115], 0
	v_mov_b64_e32 v[116:117], 0
	v_mov_b64_e32 v[118:119], 0
	v_mov_b64_e32 v[120:121], 0
	v_mov_b64_e32 v[122:123], 0
	v_mov_b64_e32 v[124:125], 0
	v_mov_b64_e32 v[126:127], 0

;     __device__ __forceinline__ bool next(int i, Unit& u) const { if (i != 0 || c >= n) return false; u.pm = pm; u.pn = c & 3; return true; }
; template <class Epi, class Sched, bool ALIGN_EPI = false, bool SP2 = false>
; __device__ __forceinline__ void gemm_phase(PG8_LAS unsigned char* lds, const Gemm g, const Sched& S, const Epi& E) {
;     ...
;         const bool has_next = S.next(ui + 1, nxt);
;         const char* nA = has_next ? (const char*)g.A + (size_t)nxt.pm * tstepA : cA; const char* nB = has_next ? (const char*)g.Bt + (size_t)nxt.pn * tstepB : cB;
;     ...
; #pragma unroll
;         for (int a = 0; a < 2; ++a)
; #pragma unroll
;             for (int b = 0; b < 2; ++b)
; #pragma unroll
;                 for (int m = 0; m < 4; ++m)
; #pragma unroll
;                     for (int n = 0; n < 2; ++n) acc[a][b][m][n] = (f32x4){0.f, 0.f, 0.f, 0.f};
;         cur = nxt; cA = nA; cB = nB; ++ui;
.LBB0_2350:
	s_ashr_i32 s11, s10, 31
	s_lshl_b64 s[18:19], s[10:11], 21
	s_add_u32 s62, s60, s18
	s_addc_u32 s63, s61, s19
	s_and_b64 s[18:19], s[2:3], exec
	s_cselect_b32 s11, s63, s93
	s_cselect_b32 s17, s62, s92
	s_ashr_i32 s9, s8, 31
	s_lshl_b64 s[18:19], s[8:9], 21
	s_add_u32 s96, s59, s18
	s_addc_u32 s97, s35, s19
	s_and_b64 s[18:19], s[2:3], exec
	s_cselect_b32 s9, s97, s43
	s_cselect_b32 s25, s96, s42
	s_add_u32 vcc_lo, s92, 0x100080
	s_addc_u32 vcc_hi, s93, 0
	s_add_u32 s27, s42, 0x100
	v_mov_b32_e32 v0, 0
	s_addc_u32 s42, s43, 0
	s_mov_b32 s43, -2
	v_mov_b64_e32 v[0:1], 0
	v_mov_b64_e32 v[2:3], 0
	v_mov_b64_e32 v[4:5], 0
	v_mov_b64_e32 v[6:7], 0
	v_mov_b64_e32 v[8:9], 0
	v_mov_b64_e32 v[10:11], 0
	v_mov_b64_e32 v[12:13], 0
	v_mov_b64_e32 v[14:15], 0
	v_mov_b64_e32 v[16:17], 0
	v_mov_b64_e32 v[18:19], 0
	v_mov_b64_e32 v[20:21], 0
	v_mov_b64_e32 v[22:23], 0
	v_mov_b64_e32 v[24:25], 0
	v_mov_b64_e32 v[26:27], 0
	v_mov_b64_e32 v[28:29], 0
	v_mov_b64_e32 v[30:31], 0
	v_mov_b64_e32 v[32:33], 0
	v_mov_b64_e32 v[34:35], 0
	v_mov_b64_e32 v[36:37], 0
	v_mov_b64_e32 v[38:39], 0
	v_mov_b64_e32 v[40:41], 0
	v_mov_b64_e32 v[42:43], 0
	v_mov_b64_e32 v[44:45], 0
	v_mov_b64_e32 v[46:47], 0
	v_mov_b64_e32 v[48:49], 0
	v_mov_b64_e32 v[50:51], 0
	v_mov_b64_e32 v[52:53], 0
	v_mov_b64_e32 v[54:55], 0
	v_mov_b64_e32 v[56:57], 0
	v_mov_b64_e32 v[58:59], 0
	v_mov_b64_e32 v[60:61], 0
	v_mov_b64_e32 v[62:63], 0
	v_mov_b64_e32 v[64:65], 0
	v_mov_b64_e32 v[66:67], 0
	v_mov_b64_e32 v[68:69], 0
	v_mov_b64_e32 v[70:71], 0
	v_mov_b64_e32 v[72:73], 0
	v_mov_b64_e32 v[74:75], 0
	v_mov_b64_e32 v[76:77], 0
	v_mov_b64_e32 v[78:79], 0
	v_mov_b64_e32 v[80:81], 0
	v_mov_b64_e32 v[82:83], 0
	v_mov_b64_e32 v[84:85], 0
	v_mov_b64_e32 v[86:87], 0
	v_mov_b64_e32 v[88:89], 0
	v_mov_b64_e32 v[90:91], 0
	v_mov_b64_e32 v[92:93], 0
	v_mov_b64_e32 v[94:95], 0
	v_mov_b64_e32 v[96:97], 0
	v_mov_b64_e32 v[98:99], 0
	v_mov_b64_e32 v[100:101], 0
	v_mov_b64_e32 v[102:103], 0
	v_mov_b64_e32 v[104:105], 0
	v_mov_b64_e32 v[106:107], 0
	v_mov_b64_e32 v[108:109], 0
	v_mov_b64_e32 v[110:111], 0
	v_mov_b64_e32 v[112:113], 0
	v_mov_b64_e32 v[114:115], 0
	v_mov_b64_e32 v[116:117], 0
	v_mov_b64_e32 v[118:119], 0
	v_mov_b64_e32 v[120:121], 0
	v_mov_b64_e32 v[122:123], 0
	v_mov_b64_e32 v[124:125], 0
	v_mov_b64_e32 v[126:127], 0
